# lever 6: LDS bank conflicts in the remapped C*B^T tile writes removed (row order within a wave steps by 4 rows per lane quad)
# speedup vs baseline: 1.0019x; 1.0019x over previous
; DI void ssd_scan_phase(bf16_t* P, const bf16_t* BT, const bf16_t* Cc, const bf16_t* CB, const float* dt, const float* acs,
;                        const float* cw, const float* cb, const float* Dp, char* lds, bool dry, int mode, float* Sbuf) {
;     ...
;       const size_t cbis = cbi0 + (size_t)c0 * 65536;
;       const bf16_t* Cq = Cc + cbis; const bf16_t* Bq = BT + cbis; const bf16_t* CBq = CB + cbis;
; #pragma unroll
;       for (int j = 0; j < 4; ++j) { rB[j] = *(const u32x4*)(Bq + toff + j * 4096); rC[j] = (u32x4){0u, 0u, 0u, 0u}; rCB[j] = (u32x4){0u, 0u, 0u, 0u};
;         if (mode == 0) { rC[j] = *(const u32x4*)(Cq + toff + j * 4096); rCB[j] = *(const u32x4*)(CBq + toff + j * 4096); } }
.LBB0_1027:
	s_or_b64 exec, exec, s[56:57]
	s_ashr_i32 s78, s68, 7
	s_lshl_b32 s80, s78, s37
	s_ashr_i32 s81, s80, 31
	s_lshl_b32 s56, s34, 22
	s_lshl_b32 s57, s69, 14
	s_or_b32 s76, s56, s57
	s_lshl_b64 s[56:57], s[80:81], 16
	s_add_u32 s56, s56, s76
	s_addc_u32 s57, s57, 0
	s_lshl_b64 s[70:71], s[56:57], 1
	v_lshl_add_u64 v[22:23], v[142:143], 0, s[70:71]
	global_load_dwordx4 v[60:63], v[22:23], off
	v_cndmask_b32_e64 v0, 0, 1, s[60:61]
	s_mov_b32 s77, s35
	v_lshl_add_u64 v[20:21], v[144:145], 0, s[70:71]
	v_cmp_ne_u32_e64 s[56:57], 1, v0
	s_andn2_b64 vcc, exec, s[60:61]
	v_lshl_add_u64 v[24:25], v[146:147], 0, s[70:71]
	s_cbranch_vccnz .LBB0_1029
	global_load_dwordx4 v[52:55], v[24:25], off
	v_lshrrev_b32_e32 v26, 4, v200
	v_and_b32_e32 v27, 15, v200
	v_lshlrev_b32_e32 v27, 4, v27
	v_lshl_or_b32 v26, v26, 8, v27
	v_sub_co_u32_e32 v26, vcc, v20, v26
	s_nop 1
	v_subbrev_co_u32_e32 v27, vcc, 0, v21, vcc
	v_lshrrev_b32_e32 v28, 2, v200
	v_and_b32_e32 v29, 3, v28
	v_bfe_u32 v46, v28, 2, 2
	v_and_b32_e32 v28, 0x70, v28
	v_lshl_or_b32 v28, v29, 2, v28
	v_or_b32_e32 v28, v28, v46
	v_sub_u32_e32 v28, 0x7f, v28
	v_and_b32_e32 v29, 3, v200
	v_lshlrev_b32_e32 v29, 4, v29
	v_lshl_or_b32 v28, v28, 8, v29
	v_add_co_u32_e32 v26, vcc, v26, v28
	s_nop 1
	v_addc_co_u32_e32 v27, vcc, 0, v27, vcc
	global_load_dwordx4 v[56:59], v[26:27], off
	s_branch .LBB0_1030

; DI void ssd_scan_phase(bf16_t* P, const bf16_t* BT, const bf16_t* Cc, const bf16_t* CB, const float* dt, const float* acs,
;                        const float* cw, const float* cb, const float* Dp, char* lds, bool dry, int mode, float* Sbuf) {
;     ...
;       if (c + 1 < c1) {
;         if (c + 2 < c1 && tid < 128) { nacs = (acs + (t0 + 256) * 32 + hh)[tid * 32]; ndt = (dt + (t0 + 256) * 32 + hh)[tid * 32]; }
;         const size_t cbi = cbi0 + (size_t)(c + 1) * 65536;
;         const bf16_t* Cq = Cc + cbi; const bf16_t* Bq = BT + cbi; const bf16_t* CBq = CB + cbi;
; #pragma unroll
;         for (int j = 0; j < 4; ++j) { rB[j] = *(const u32x4*)(Bq + toff + j * 4096); if (mode == 0) { rC[j] = *(const u32x4*)(Cq + toff + j * 4096); rCB[j] = *(const u32x4*)(CBq + toff + j * 4096); } }
.LBB0_1085:
	s_or_b64 exec, exec, s[80:81]
	s_and_b64 vcc, exec, s[56:57]
	s_add_u32 s100, s74, 0x20000
	s_addc_u32 s101, s75, 0
	global_load_dwordx4 v[60:63], v168, s[100:101]
	s_cbranch_vccnz .Ls2_m1
	s_add_u32 s100, s74, 0x1020000
	s_addc_u32 s101, s75, 0
	global_load_dwordx4 v[52:55], v168, s[100:101]
	v_lshrrev_b32_e32 v26, 4, v200
	v_and_b32_e32 v27, 15, v200
	v_lshlrev_b32_e32 v27, 4, v27
	v_lshl_or_b32 v26, v26, 8, v27
	v_sub_u32_e32 v26, v168, v26
	v_lshrrev_b32_e32 v28, 2, v200
	v_and_b32_e32 v29, 3, v28
	v_bfe_u32 v46, v28, 2, 2
	v_and_b32_e32 v28, 0x70, v28
	v_lshl_or_b32 v28, v29, 2, v28
	v_or_b32_e32 v28, v28, v46
	v_sub_u32_e32 v28, 0x7f, v28
	v_and_b32_e32 v29, 3, v200
	v_lshlrev_b32_e32 v29, 4, v29
	v_lshl_or_b32 v28, v28, 8, v29
	v_add_u32_e32 v26, v26, v28
	s_add_u32 s100, s76, 0x20000
	s_addc_u32 s101, s77, 0
	global_load_dwordx4 v[56:59], v26, s[100:101]
	s_add_u32 s100, s74, 0x22000
	s_addc_u32 s101, s75, 0
	global_load_dwordx4 v[76:79], v168, s[100:101]
	s_add_u32 s100, s74, 0x1022000
	s_addc_u32 s101, s75, 0
	global_load_dwordx4 v[64:67], v168, s[100:101]
	s_add_u32 s100, s76, 0x20000
	s_addc_u32 s101, s77, 0
	global_load_dwordx4 v[68:71], v26, s[100:101] offset:64
	s_add_u32 s100, s74, 0x24000
	s_addc_u32 s101, s75, 0
	global_load_dwordx4 v[92:95], v168, s[100:101]
	s_add_u32 s100, s74, 0x1024000
	s_addc_u32 s101, s75, 0
	global_load_dwordx4 v[72:75], v168, s[100:101]
	s_add_u32 s100, s76, 0x20000
	s_addc_u32 s101, s77, 0
	global_load_dwordx4 v[80:83], v26, s[100:101] offset:128
	s_add_u32 s100, s74, 0x26000
	s_addc_u32 s101, s75, 0
	global_load_dwordx4 v[104:107], v168, s[100:101]
	s_add_u32 s100, s74, 0x1026000
	s_addc_u32 s101, s75, 0
	global_load_dwordx4 v[84:87], v168, s[100:101]
	s_add_u32 s100, s76, 0x20000
	s_addc_u32 s101, s77, 0
	global_load_dwordx4 v[88:91], v26, s[100:101] offset:192
	s_branch .LBB0_1093

; DI u32x4 pack8(const float (&f)[8]) { u32x4 r; r[0] = pk2(f[0], f[1]); r[1] = pk2(f[2], f[3]); r[2] = pk2(f[4], f[5]); r[3] = pk2(f[6], f[7]); return r; }
; DI void ssd_scan_phase(bf16_t* P, const bf16_t* BT, const bf16_t* Cc, const bf16_t* CB, const float* dt, const float* acs,
;                        const float* cw, const float* cb, const float* Dp, char* lds, bool dry, int mode, float* Sbuf) {
;     ...
;         const f32x4 a0 = *(const f32x4*)(cAcs + cch * 8), a1 = *(const f32x4*)(cAcs + cch * 8 + 4);
;         const float L2E = 1.44269504f;
;         const float as[8] = {a0[0] * L2E, a0[1] * L2E, a0[2] * L2E, a0[3] * L2E, a1[0] * L2E, a1[1] * L2E, a1[2] * L2E, a1[3] * L2E};
; #pragma unroll
;         for (int j = 0; j < 4; ++j) {
;           const int r = r0 + 32 * j;
;           *(u32x4*)(sBT + swz128(r, cch)) = rB[j];
;           if (mode == 0) {
;             *(u32x4*)(sC + swz128(r, cch)) = rC[j];
;             float f[8]; unpack8(rCB[j], f);
;             const float el = cAcs[r] * L2E;
;             const int lim = r - cch * 8;
; #pragma unroll
;             for (int e = 0; e < 8; ++e) f[e] = (e <= lim) ? f[e] * __builtin_amdgcn_exp2f(el - as[e]) : 0.f;
;             *(u32x4*)(sCBL + swz128(r, cch)) = pack8(f);
.Ls1n:
	v_bitop3_b32 v30, v29, v34, 15 bitop3:0x6c
	v_lshlrev_b32_e32 v30, 4, v30
	v_lshl_add_u32 v33, v29, 8, v30
	v_add_u32_e32 v31, 0x10000, v33
	v_lshrrev_b32_e32 v20, 2, v200
	v_and_b32_e32 v22, 3, v20
	v_bfe_u32 v23, v20, 2, 2
	v_and_b32_e32 v20, 0x70, v20
	v_lshl_or_b32 v20, v22, 2, v20
	v_or_b32_e32 v20, v20, v23
	v_sub_u32_e32 v20, 0x7f, v20
	v_and_b32_e32 v21, 3, v200
	v_lshl_add_u32 v22, v20, 2, s88
	ds_read_b32 v48, v22
	v_lshl_add_u32 v23, v21, 5, s88
	v_lshlrev_b32_e32 v24, 8, v20
	v_and_b32_e32 v25, 15, v20
	v_lshlrev_b32_e32 v26, 3, v21
	v_sub_u32_e32 v26, v20, v26
	v_readfirstlane_b32 s78, v200
	s_lshr_b32 s78, s78, 6
	s_cmp_lg_u64 s[42:43], 0
	s_cbranch_scc1 .Ls1n_w47_0
	s_waitcnt vmcnt(17)
	s_branch .Ls1n_wd_0
